# compressed-branch importance blocks: group pairs wholly beyond the current block skipped
# baseline (speedup 1.0000x reference)
; #define MFMA16(a, b, c) __builtin_amdgcn_mfma_f32_16x16x32_f16((a), (b), (c), 0, 0, 0)
; DI float lane_get(float v, int srclane) { return __int_as_float(__builtin_amdgcn_ds_bpermute(srclane << 2, __float_as_int(v))); }
; #define LAS __attribute__((address_space(3)))
; DI float red4_sum(float v, int lane) { v += lane_get(v, lane ^ 16); v += lane_get(v, lane ^ 32); return v; }
; DI void attn_phase(const Params& p, const int layer, const int wid_s) {
;     ...
;         ps = red4_sum(ps, lane);
;         const float inv = ps > 0.f ? 1.f / ps : 0.f;
; #pragma unroll
;         for (int nt = 0; nt < 8; ++nt) s[nt] = s[nt] * inv;
;         if (cur >= 8)
; #pragma unroll
;         for (int nt = 0; nt < 8; ++nt) {
;           const float x1 = lane_get(s[nt][3], (lane - 16) & 63);
;           const float x2 = nt > 0 ? lane_get(s[nt > 0 ? nt - 1 : 0][3], (lane - 16) & 63) : 0.f;
;           const float left = fq > 0 ? x1 : x2;
;           const float im = left + 2.f * (s[nt][0] + s[nt][1] + s[nt][2]) + s[nt][3];
;           LAS float* ip = impx + (wave * 8 + nt) * 64;
;           if (hp == 0) *ip = im; else *ip += im;
;         }
;         f32x4 o[4];
; #pragma unroll
;         for (int dt = 0; dt < 4; ++dt) o[dt] = (f32x4){0.f, 0.f, 0.f, 0.f};
; #pragma unroll
;         for (int st = 0; st < 4; ++st) {
;           if (2 * st * 256 > t0 - 16) continue;
;           const half8 pf = {(h16)s[2 * st][0], (h16)s[2 * st][1], (h16)s[2 * st][2], (h16)s[2 * st][3],
;                             (h16)s[2 * st + 1][0], (h16)s[2 * st + 1][1], (h16)s[2 * st + 1][2], (h16)s[2 * st + 1][3]};
; #pragma unroll
;           for (int dt = 0; dt < 4; ++dt) {
;             const half8 vf = *(const half8*)(vcb + ((st * 64) + dt * 16 + fr) * 32 + fq * 8);
;             o[dt] = MFMA16(vf, pf, o[dt]);
;           }
.LBB0_264:
	v_mov_b32_e32 v0, v5
	s_cmp_gt_i32 s54, 7
	v_add_u32_e32 v151, s64, v177
	s_cselect_b64 s[12:13], -1, 0
	s_cmp_lt_i32 s54, 8
	s_waitcnt lgkmcnt(0)
	s_nop 1
	v_permlane16_swap_b32_e32 v0, v5
	v_add_f32_e32 v0, v5, v0
	v_mov_b32_e32 v5, v0
	v_add_u32_e32 v155, 0x80, v151
	s_waitcnt lgkmcnt(0)
	s_nop 1
	v_permlane32_swap_b32_e32 v5, v0
	v_add_f32_e32 v0, v0, v5
	v_div_scale_f32 v5, s[14:15], v0, v0, 1.0
	v_rcp_f32_e32 v114, v5
	v_div_scale_f32 v115, vcc, 1.0, v0, 1.0
	v_fma_f32 v116, -v5, v114, 1.0
	v_fmac_f32_e32 v114, v116, v114
	v_mul_f32_e32 v116, v115, v114
	v_fma_f32 v117, -v5, v116, v115
	v_fmac_f32_e32 v116, v117, v114
	v_fma_f32 v5, -v5, v116, v115
	v_div_fmas_f32 v5, v5, v114, v116
	v_div_fixup_f32 v5, v5, v0, 1.0
	v_cmp_lt_f32_e32 vcc, 0, v0
	s_nop 1
	v_cndmask_b32_e32 v0, 0, v5, vcc
	v_pk_mul_f32 v[134:135], v[124:125], v[0:1] op_sel_hi:[1,0]
	v_pk_mul_f32 v[152:153], v[6:7], v[0:1] op_sel_hi:[1,0]
	v_pk_mul_f32 v[88:89], v[88:89], v[0:1] op_sel_hi:[1,0]
	v_pk_mul_f32 v[2:3], v[2:3], v[0:1] op_sel_hi:[1,0]
	v_pk_mul_f32 v[126:127], v[94:95], v[0:1] op_sel_hi:[1,0]
	v_pk_mul_f32 v[128:129], v[92:93], v[0:1] op_sel_hi:[1,0]
	v_pk_mul_f32 v[130:131], v[96:97], v[0:1] op_sel_hi:[1,0]
	v_pk_mul_f32 v[132:133], v[90:91], v[0:1] op_sel_hi:[1,0]
	v_pk_mul_f32 v[114:115], v[102:103], v[0:1] op_sel_hi:[1,0]
	v_pk_mul_f32 v[116:117], v[100:101], v[0:1] op_sel_hi:[1,0]
	v_pk_mul_f32 v[118:119], v[104:105], v[0:1] op_sel_hi:[1,0]
	v_pk_mul_f32 v[124:125], v[98:99], v[0:1] op_sel_hi:[1,0]
	v_pk_mul_f32 v[6:7], v[110:111], v[0:1] op_sel_hi:[1,0]
	v_pk_mul_f32 v[108:109], v[108:109], v[0:1] op_sel_hi:[1,0]
	v_pk_mul_f32 v[110:111], v[112:113], v[0:1] op_sel_hi:[1,0]
	v_pk_mul_f32 v[112:113], v[106:107], v[0:1] op_sel_hi:[1,0]
	s_cbranch_scc1 .LBB0_266
	ds_bpermute_b32 v198, v181, v135
	ds_bpermute_b32 v199, v181, v89
	ds_bpermute_b32 v200, v181, v127
	ds_bpermute_b32 v201, v181, v131
	ds_bpermute_b32 v202, v181, v115
	ds_bpermute_b32 v203, v181, v119
	ds_bpermute_b32 v204, v181, v7
	ds_bpermute_b32 v205, v181, v111
	s_waitcnt lgkmcnt(0)
	v_add_f32_e32 v5, v152, v153
	v_add_f32_e32 v5, v134, v5
	v_add_f32_e32 v91, v2, v3
	v_add_f32_e32 v91, v88, v91
	v_cndmask_b32_e64 v92, v198, 0, s[62:63]
	v_fmac_f32_e32 v92, 2.0, v5
	v_add_f32_e32 v5, v135, v92
	v_cndmask_b32_e64 v0, v199, v198, s[62:63]
	v_fmac_f32_e32 v0, 2.0, v91
	v_add_f32_e32 v0, v89, v0
	ds_write2st64_b32 v155, v5, v0 offset0:88 offset1:89
	v_add_f32_e32 v5, v128, v129
	v_add_f32_e32 v5, v126, v5
	v_add_f32_e32 v91, v132, v133
	v_add_f32_e32 v91, v130, v91
	v_cndmask_b32_e64 v92, v200, v199, s[62:63]
	v_fmac_f32_e32 v92, 2.0, v5
	v_add_f32_e32 v5, v127, v92
	v_cndmask_b32_e64 v0, v201, v200, s[62:63]
	v_fmac_f32_e32 v0, 2.0, v91
	v_add_f32_e32 v0, v131, v0
	ds_write2st64_b32 v155, v5, v0 offset0:90 offset1:91
	s_cmp_lt_i32 s54, 16
	s_cbranch_scc1 .Limp_end_a
	v_add_f32_e32 v5, v116, v117
	v_add_f32_e32 v5, v114, v5
	v_add_f32_e32 v91, v124, v125
	v_add_f32_e32 v91, v118, v91
	v_cndmask_b32_e64 v92, v202, v201, s[62:63]
	v_fmac_f32_e32 v92, 2.0, v5
	v_add_f32_e32 v5, v115, v92
	v_cndmask_b32_e64 v0, v203, v202, s[62:63]
	v_fmac_f32_e32 v0, 2.0, v91
	v_add_f32_e32 v0, v119, v0
	ds_write2st64_b32 v155, v5, v0 offset0:92 offset1:93
	s_cmp_lt_i32 s54, 24
	s_cbranch_scc1 .Limp_end_a
	v_add_f32_e32 v5, v108, v109
	v_add_f32_e32 v5, v6, v5
	v_add_f32_e32 v91, v112, v113
	v_add_f32_e32 v91, v110, v91
	v_cndmask_b32_e64 v92, v204, v203, s[62:63]
	v_fmac_f32_e32 v92, 2.0, v5
	v_add_f32_e32 v5, v7, v92
	v_cndmask_b32_e64 v0, v205, v204, s[62:63]
	v_fmac_f32_e32 v0, 2.0, v91
	v_add_f32_e32 v0, v111, v0
	ds_write2st64_b32 v155, v5, v0 offset0:94 offset1:95
.Limp_end_a:
.LBB0_266:
	v_lshl_add_u64 v[104:105], v[142:143], 0, s[10:11]
	v_lshlrev_b32_e32 v246, 1, v148
	v_add_co_u32_e32 v246, vcc, v104, v246
	s_nop 1
	v_addc_co_u32_e32 v247, vcc, 0, v105, vcc
	v_add_co_u32_e32 v246, vcc, 0x2000, v246
	s_nop 1
	v_addc_co_u32_e32 v247, vcc, 0, v247, vcc
	v_add_co_u32_e32 v254, vcc, 0x1000, v246
	s_nop 1
	v_addc_co_u32_e32 v255, vcc, 0, v247, vcc
	global_load_dwordx4 v[198:201], v[246:247], off offset:-4096
	global_load_dwordx4 v[202:205], v[246:247], off offset:-3072
	global_load_dwordx4 v[206:209], v[246:247], off offset:-2048
	global_load_dwordx4 v[210:213], v[246:247], off offset:-1024
	global_load_dwordx4 v[214:217], v[246:247], off
	global_load_dwordx4 v[218:221], v[246:247], off offset:1024
	global_load_dwordx4 v[222:225], v[246:247], off offset:2048
	global_load_dwordx4 v[226:229], v[246:247], off offset:3072
	global_load_dwordx4 v[230:233], v[254:255], off
	global_load_dwordx4 v[234:237], v[254:255], off offset:1024
	global_load_dwordx4 v[238:241], v[254:255], off offset:2048
	global_load_dwordx4 v[242:245], v[254:255], off offset:3072
	s_and_b64 vcc, exec, s[40:41]
	v_lshlrev_b32_e32 v106, 1, v148
	s_cbranch_vccnz .LBB0_286
	v_mov_b32_e32 v107, v1
	v_lshl_add_u64 v[98:99], v[104:105], 0, v[106:107]
	flat_load_dwordx4 v[90:93], v[98:99]
	flat_load_dwordx4 v[94:97], v[98:99] offset:1024
	v_cvt_pk_f16_f32 v193, v88, v89
	v_cvt_pk_f16_f32 v192, v2, v3
	v_cvt_pk_f16_f32 v191, v134, v135
	v_cvt_pk_f16_f32 v190, v152, v153
	flat_load_dwordx4 v[194:197], v[98:99] offset:3072
	s_waitcnt vmcnt(0) lgkmcnt(0)
	v_mfma_f32_16x16x32_f16 v[100:103], v[90:93], v[190:193], 0
	flat_load_dwordx4 v[88:91], v[98:99] offset:2048
	v_mfma_f32_16x16x32_f16 v[92:95], v[94:97], v[190:193], 0
	s_waitcnt vmcnt(0) lgkmcnt(0)
	v_mfma_f32_16x16x32_f16 v[96:99], v[88:91], v[190:193], 0
	v_mfma_f32_16x16x32_f16 v[88:91], v[194:197], v[190:193], 0
	s_and_b64 vcc, exec, s[42:43]
	s_cbranch_vccnz .LBB0_269

; #define MFMA16(a, b, c) __builtin_amdgcn_mfma_f32_16x16x32_f16((a), (b), (c), 0, 0, 0)
; DI float lane_get(float v, int srclane) { return __int_as_float(__builtin_amdgcn_ds_bpermute(srclane << 2, __float_as_int(v))); }
; #define LAS __attribute__((address_space(3)))
; DI float red4_sum(float v, int lane) { v += lane_get(v, lane ^ 16); v += lane_get(v, lane ^ 32); return v; }
; DI void attn_phase(const Params& p, const int layer, const int wid_s) {
;     ...
;         ps = red4_sum(ps, lane);
;         const float inv = ps > 0.f ? 1.f / ps : 0.f;
; #pragma unroll
;         for (int nt = 0; nt < 8; ++nt) s[nt] = s[nt] * inv;
;         if (cur >= 8)
; #pragma unroll
;         for (int nt = 0; nt < 8; ++nt) {
;           const float x1 = lane_get(s[nt][3], (lane - 16) & 63);
;           const float x2 = nt > 0 ? lane_get(s[nt > 0 ? nt - 1 : 0][3], (lane - 16) & 63) : 0.f;
;           const float left = fq > 0 ? x1 : x2;
;           const float im = left + 2.f * (s[nt][0] + s[nt][1] + s[nt][2]) + s[nt][3];
;           LAS float* ip = impx + (wave * 8 + nt) * 64;
;           if (hp == 0) *ip = im; else *ip += im;
;         }
;         f32x4 o[4];
; #pragma unroll
;         for (int dt = 0; dt < 4; ++dt) o[dt] = (f32x4){0.f, 0.f, 0.f, 0.f};
; #pragma unroll
;         for (int st = 0; st < 4; ++st) {
;           if (2 * st * 256 > t0 - 16) continue;
;           const half8 pf = {(h16)s[2 * st][0], (h16)s[2 * st][1], (h16)s[2 * st][2], (h16)s[2 * st][3],
;                             (h16)s[2 * st + 1][0], (h16)s[2 * st + 1][1], (h16)s[2 * st + 1][2], (h16)s[2 * st + 1][3]};
; #pragma unroll
;           for (int dt = 0; dt < 4; ++dt) {
;             const half8 vf = *(const half8*)(vcb + ((st * 64) + dt * 16 + fr) * 32 + fq * 8);
;             o[dt] = MFMA16(vf, pf, o[dt]);
;           }
.LBB0_324:
	v_mov_b32_e32 v0, v5
	s_waitcnt lgkmcnt(0)
	s_nop 1
	v_permlane16_swap_b32_e32 v0, v5
	v_add_f32_e32 v0, v5, v0
	v_mov_b32_e32 v5, v0
	s_waitcnt lgkmcnt(0)
	s_nop 1
	v_permlane32_swap_b32_e32 v5, v0
	v_add_f32_e32 v0, v0, v5
	v_div_scale_f32 v5, s[0:1], v0, v0, 1.0
	v_rcp_f32_e32 v24, v5
	v_div_scale_f32 v25, vcc, 1.0, v0, 1.0
	v_fma_f32 v26, -v5, v24, 1.0
	v_fmac_f32_e32 v24, v26, v24
	v_mul_f32_e32 v26, v25, v24
	v_fma_f32 v27, -v5, v26, v25
	v_fmac_f32_e32 v26, v27, v24
	v_fma_f32 v5, -v5, v26, v25
	v_div_fmas_f32 v5, v5, v24, v26
	v_div_fixup_f32 v5, v5, v0, 1.0
	v_cmp_lt_f32_e32 vcc, 0, v0
	s_nop 1
	v_cndmask_b32_e32 v0, 0, v5, vcc
	v_cndmask_b32_e64 v5, 0, 1, s[12:13]
	v_pk_mul_f32 v[2:3], v[2:3], v[0:1] op_sel_hi:[1,0]
	v_pk_mul_f32 v[24:25], v[28:29], v[0:1] op_sel_hi:[1,0]
	v_pk_mul_f32 v[26:27], v[30:31], v[0:1] op_sel_hi:[1,0]
	v_pk_mul_f32 v[28:29], v[6:7], v[0:1] op_sel_hi:[1,0]
	v_pk_mul_f32 v[54:55], v[44:45], v[0:1] op_sel_hi:[1,0]
	v_pk_mul_f32 v[56:57], v[38:39], v[0:1] op_sel_hi:[1,0]
	v_pk_mul_f32 v[58:59], v[46:47], v[0:1] op_sel_hi:[1,0]
	v_pk_mul_f32 v[60:61], v[36:37], v[0:1] op_sel_hi:[1,0]
	v_pk_mul_f32 v[46:47], v[50:51], v[0:1] op_sel_hi:[1,0]
	v_pk_mul_f32 v[48:49], v[48:49], v[0:1] op_sel_hi:[1,0]
	v_pk_mul_f32 v[50:51], v[40:41], v[0:1] op_sel_hi:[1,0]
	v_pk_mul_f32 v[52:53], v[52:53], v[0:1] op_sel_hi:[1,0]
	v_pk_mul_f32 v[6:7], v[34:35], v[0:1] op_sel_hi:[1,0]
	v_pk_mul_f32 v[40:41], v[32:33], v[0:1] op_sel_hi:[1,0]
	v_pk_mul_f32 v[42:43], v[42:43], v[0:1] op_sel_hi:[1,0]
	v_cmp_ne_u32_e64 s[0:1], 1, v5
	s_andn2_b64 vcc, exec, s[12:13]
	v_pk_mul_f32 v[44:45], v[62:63], v[0:1] op_sel_hi:[1,0]
	s_cbranch_vccnz .LBB0_326
	ds_bpermute_b32 v84, v181, v3
	ds_bpermute_b32 v85, v181, v27
	ds_bpermute_b32 v86, v181, v55
	ds_bpermute_b32 v87, v181, v59
	ds_bpermute_b32 v88, v181, v47
	ds_bpermute_b32 v89, v181, v51
	ds_bpermute_b32 v90, v181, v7
	ds_bpermute_b32 v91, v181, v43
	ds_read2st64_b32 v[92:93], v155 offset0:88 offset1:89
	ds_read2st64_b32 v[94:95], v155 offset0:90 offset1:91
	ds_read2st64_b32 v[96:97], v155 offset0:92 offset1:93
	ds_read2st64_b32 v[98:99], v155 offset0:94 offset1:95
	s_waitcnt lgkmcnt(0)
	v_add_f32_e32 v5, v24, v25
	v_add_f32_e32 v5, v2, v5
	v_add_f32_e32 v32, v28, v29
	v_add_f32_e32 v32, v26, v32
	v_cndmask_b32_e64 v30, v84, 0, s[62:63]
	v_fmac_f32_e32 v30, 2.0, v5
	v_add_f32_e32 v5, v3, v30
	v_add_f32_e32 v5, v92, v5
	v_cndmask_b32_e64 v0, v85, v84, s[62:63]
	v_fmac_f32_e32 v0, 2.0, v32
	v_add_f32_e32 v0, v27, v0
	v_add_f32_e32 v0, v93, v0
	ds_write2st64_b32 v155, v5, v0 offset0:88 offset1:89
	v_add_f32_e32 v5, v56, v57
	v_add_f32_e32 v5, v54, v5
	v_add_f32_e32 v32, v60, v61
	v_add_f32_e32 v32, v58, v32
	v_cndmask_b32_e64 v30, v86, v85, s[62:63]
	v_fmac_f32_e32 v30, 2.0, v5
	v_add_f32_e32 v5, v55, v30
	v_add_f32_e32 v5, v94, v5
	v_cndmask_b32_e64 v0, v87, v86, s[62:63]
	v_fmac_f32_e32 v0, 2.0, v32
	v_add_f32_e32 v0, v59, v0
	v_add_f32_e32 v0, v95, v0
	ds_write2st64_b32 v155, v5, v0 offset0:90 offset1:91
	s_cmp_lt_i32 s54, 16
	s_cbranch_scc1 .Limp_end_b
	v_add_f32_e32 v5, v48, v49
	v_add_f32_e32 v5, v46, v5
	v_add_f32_e32 v32, v52, v53
	v_add_f32_e32 v32, v50, v32
	v_cndmask_b32_e64 v30, v88, v87, s[62:63]
	v_fmac_f32_e32 v30, 2.0, v5
	v_add_f32_e32 v5, v47, v30
	v_add_f32_e32 v5, v96, v5
	v_cndmask_b32_e64 v0, v89, v88, s[62:63]
	v_fmac_f32_e32 v0, 2.0, v32
	v_add_f32_e32 v0, v51, v0
	v_add_f32_e32 v0, v97, v0
	ds_write2st64_b32 v155, v5, v0 offset0:92 offset1:93
	s_cmp_lt_i32 s54, 24
	s_cbranch_scc1 .Limp_end_b
	v_add_f32_e32 v5, v40, v41
	v_add_f32_e32 v5, v6, v5
	v_add_f32_e32 v32, v44, v45
	v_add_f32_e32 v32, v42, v32
	v_cndmask_b32_e64 v30, v90, v89, s[62:63]
	v_fmac_f32_e32 v30, 2.0, v5
	v_add_f32_e32 v5, v7, v30
	v_add_f32_e32 v5, v98, v5
	v_cndmask_b32_e64 v0, v91, v90, s[62:63]
	v_fmac_f32_e32 v0, 2.0, v32
	v_add_f32_e32 v0, v43, v0
	v_add_f32_e32 v0, v99, v0
	ds_write2st64_b32 v155, v5, v0 offset0:94 offset1:95
.Limp_end_b:
.LBB0_326:
	s_and_b64 vcc, exec, s[40:41]
	s_cbranch_vccnz .LBB0_373
	v_mov_b32_e32 v107, v1
	v_lshl_add_u64 v[34:35], v[104:105], 0, v[106:107]
	flat_load_dwordx4 v[30:33], v[34:35]
	flat_load_dwordx4 v[62:65], v[34:35] offset:1024
	v_cvt_pk_f16_f32 v69, v26, v27
	v_cvt_pk_f16_f32 v68, v28, v29
	v_cvt_pk_f16_f32 v67, v2, v3
	v_cvt_pk_f16_f32 v66, v24, v25
	flat_load_dwordx4 v[24:27], v[34:35] offset:2048
	s_waitcnt vmcnt(0) lgkmcnt(0)
	v_mfma_f32_16x16x32_f16 v[36:39], v[30:33], v[66:69], 0
	v_mfma_f32_16x16x32_f16 v[28:31], v[62:65], v[66:69], 0
	flat_load_dwordx4 v[62:65], v[34:35] offset:3072
	v_mfma_f32_16x16x32_f16 v[32:35], v[24:27], v[66:69], 0
	s_waitcnt vmcnt(0) lgkmcnt(0)
	v_mfma_f32_16x16x32_f16 v[24:27], v[62:65], v[66:69], 0
	s_and_b64 vcc, exec, s[42:43]
	s_cbranch_vccnz .LBB0_329
